# X3 decayed-score stage branch-free (rt values prefetched with 4 ds_read_b128, mask by signed compare + cndmask) + attention K swizzle fix
# speedup vs baseline: 1.0150x; 1.0150x over previous
; DI bf16 f2bf(float x) { return (bf16)(cvtpk(x, 0.f) & 0xffffu); }
; DI int crow(int i, int h) { return (i & 3) + 8 * (i >> 2) + 4 * h; }
; DI void mlstm_x3(const Params& p, LAS unsigned char* lds, int item, int tid_in, int lane_in, int wave) {
;     ...
;         for (int tt = 0; tt < 2; ++tt) { const int tj = 2 * eh + tt; const bool need = dir ? (tj >= ti) : (tj <= ti);
;             if (need) {
;                 const int scol = 32 * tj + r; const float as = d[scol];
; #pragma unroll
;                 for (int i = 0; i < 16; ++i) { const int trow = 32 * ti + crow(i, h); const bool ok = dir ? (scol >= trow) : (scol <= trow);
;                     const float e = ok ? __expf(as + d[128 + trow]) * KSCALE : 0.f;
;                     const float sv = (i & 1) ? __uint_as_float(spk[tt][i >> 1] & 0xffff0000u) : __uint_as_float(spk[tt][i >> 1] << 16); Ss[trow * MP + scol] = f2bf(sv * e); } } }
.LBB0_707:
	v_cndmask_b32_e64 v0, 0, 1, s[20:21]
	v_cndmask_b32_e64 v1, 0, 1, s[94:95]
	v_cndmask_b32_e64 v0, v0, v1, s[38:39]
	s_lshl_b32 s4, s9, 11
	v_and_b32_e32 v0, 1, v0
	s_add_i32 s8, s4, 0
	v_mov_b32_e32 v37, v173
	v_cmp_eq_u32_e32 vcc, 0, v0
	s_waitcnt lgkmcnt(0)
	s_barrier
	s_add_i32 s8, s8, 0x22b30
	s_nop 0
	v_add_u32_e32 v38, s14, v37
	v_lshl_add_u32 v96, v188, 2, s8
	ds_read_b128 v[100:103], v96 offset:512
	ds_read_b128 v[104:107], v96 offset:544
	ds_read_b128 v[108:111], v96 offset:576
	ds_read_b128 v[112:115], v96 offset:608
	s_cbranch_vccnz .LBB0_741
	v_lshl_add_u32 v0, v38, 2, s8
	ds_read_b32 v0, v0
	s_cmp_lg_u64 s[38:39], 0
	s_cselect_b32 s98, 1, -1
	v_lshl_add_u32 v1, v38, 1, v192
	s_waitcnt lgkmcnt(0)
	v_add_f32_e32 v116, v0, v100
	v_add_f32_e32 v118, v0, v101
	v_mul_f32_e32 v116, 0x3fb8aa3b, v116
	v_mul_f32_e32 v118, 0x3fb8aa3b, v118
	v_exp_f32_e32 v116, v116
	v_exp_f32_e32 v118, v118
	v_sub_u32_e32 v117, v38, v188
	v_sub_u32_e32 v119, v38, v187
	v_mul_i32_i24_e32 v117, s98, v117
	v_mul_i32_i24_e32 v119, s98, v119
	v_cmp_gt_i32_e32 vcc, 1, v117
	v_cmp_gt_i32_e64 s[4:5], 1, v119
	v_mul_f32_e32 v116, 0x3db504f3, v116
	v_mul_f32_e32 v118, 0x3db504f3, v118
	v_cndmask_b32_e32 v116, 0, v116, vcc
	v_cndmask_b32_e64 v118, 0, v118, s[4:5]
	v_mul_f32_e32 v116, v116, v191
	v_mul_f32_e32 v118, v118, v193
	v_cvt_pk_bf16_f32 v116, v116, v116
	v_cvt_pk_bf16_f32 v118, v118, v118
	ds_write_b16 v1, v116 offset:35088
	ds_write_b16 v1, v118 offset:35360
	v_add_f32_e32 v120, v0, v102
	v_add_f32_e32 v122, v0, v103
	v_mul_f32_e32 v120, 0x3fb8aa3b, v120
	v_mul_f32_e32 v122, 0x3fb8aa3b, v122
	v_exp_f32_e32 v120, v120
	v_exp_f32_e32 v122, v122
	v_sub_u32_e32 v121, v38, v186
	v_sub_u32_e32 v123, v38, v185
	v_mul_i32_i24_e32 v121, s98, v121
	v_mul_i32_i24_e32 v123, s98, v123
	v_cmp_gt_i32_e32 vcc, 1, v121
	v_cmp_gt_i32_e64 s[4:5], 1, v123
	v_mul_f32_e32 v120, 0x3db504f3, v120
	v_mul_f32_e32 v122, 0x3db504f3, v122
	v_cndmask_b32_e32 v120, 0, v120, vcc
	v_cndmask_b32_e64 v122, 0, v122, s[4:5]
	v_mul_f32_e32 v120, v120, v194
	v_mul_f32_e32 v122, v122, v195
	v_cvt_pk_bf16_f32 v120, v120, v120
	v_cvt_pk_bf16_f32 v122, v122, v122
	ds_write_b16 v1, v120 offset:35632
	ds_write_b16 v1, v122 offset:35904
	v_add_f32_e32 v124, v0, v104
	v_add_f32_e32 v126, v0, v105
	v_mul_f32_e32 v124, 0x3fb8aa3b, v124
	v_mul_f32_e32 v126, 0x3fb8aa3b, v126
	v_exp_f32_e32 v124, v124
	v_exp_f32_e32 v126, v126
	v_sub_u32_e32 v125, v38, v184
	v_sub_u32_e32 v127, v38, v183
	v_mul_i32_i24_e32 v125, s98, v125
	v_mul_i32_i24_e32 v127, s98, v127
	v_cmp_gt_i32_e32 vcc, 1, v125
	v_cmp_gt_i32_e64 s[4:5], 1, v127
	v_mul_f32_e32 v124, 0x3db504f3, v124
	v_mul_f32_e32 v126, 0x3db504f3, v126
	v_cndmask_b32_e32 v124, 0, v124, vcc
	v_cndmask_b32_e64 v126, 0, v126, s[4:5]
	v_mul_f32_e32 v124, v124, v196
	v_mul_f32_e32 v126, v126, v197
	v_cvt_pk_bf16_f32 v124, v124, v124
	v_cvt_pk_bf16_f32 v126, v126, v126
	ds_write_b16 v1, v124 offset:37264
	ds_write_b16 v1, v126 offset:37536
	v_add_f32_e32 v96, v0, v106
	v_add_f32_e32 v98, v0, v107
	v_mul_f32_e32 v96, 0x3fb8aa3b, v96
	v_mul_f32_e32 v98, 0x3fb8aa3b, v98
	v_exp_f32_e32 v96, v96
	v_exp_f32_e32 v98, v98
	v_sub_u32_e32 v97, v38, v182
	v_sub_u32_e32 v99, v38, v181
	v_mul_i32_i24_e32 v97, s98, v97
	v_mul_i32_i24_e32 v99, s98, v99
	v_cmp_gt_i32_e32 vcc, 1, v97
	v_cmp_gt_i32_e64 s[4:5], 1, v99
	v_mul_f32_e32 v96, 0x3db504f3, v96
	v_mul_f32_e32 v98, 0x3db504f3, v98
	v_cndmask_b32_e32 v96, 0, v96, vcc
	v_cndmask_b32_e64 v98, 0, v98, s[4:5]
	v_mul_f32_e32 v96, v96, v198
	v_mul_f32_e32 v98, v98, v199
	v_cvt_pk_bf16_f32 v96, v96, v96
	v_cvt_pk_bf16_f32 v98, v98, v98
	ds_write_b16 v1, v96 offset:37808
	ds_write_b16 v1, v98 offset:38080
	v_add_f32_e32 v116, v0, v108
	v_add_f32_e32 v118, v0, v109
	v_mul_f32_e32 v116, 0x3fb8aa3b, v116
	v_mul_f32_e32 v118, 0x3fb8aa3b, v118
	v_exp_f32_e32 v116, v116
	v_exp_f32_e32 v118, v118
	v_sub_u32_e32 v117, v38, v180
	v_sub_u32_e32 v119, v38, v179
	v_mul_i32_i24_e32 v117, s98, v117
	v_mul_i32_i24_e32 v119, s98, v119
	v_cmp_gt_i32_e32 vcc, 1, v117
	v_cmp_gt_i32_e64 s[4:5], 1, v119
	v_mul_f32_e32 v116, 0x3db504f3, v116
	v_mul_f32_e32 v118, 0x3db504f3, v118
	v_cndmask_b32_e32 v116, 0, v116, vcc
	v_cndmask_b32_e64 v118, 0, v118, s[4:5]
	v_mul_f32_e32 v116, v116, v200
	v_mul_f32_e32 v118, v118, v201
	v_cvt_pk_bf16_f32 v116, v116, v116
	v_cvt_pk_bf16_f32 v118, v118, v118
	ds_write_b16 v1, v116 offset:39440
	ds_write_b16 v1, v118 offset:39712
	v_add_f32_e32 v120, v0, v110
	v_add_f32_e32 v122, v0, v111
	v_mul_f32_e32 v120, 0x3fb8aa3b, v120
	v_mul_f32_e32 v122, 0x3fb8aa3b, v122
	v_exp_f32_e32 v120, v120
	v_exp_f32_e32 v122, v122
	v_sub_u32_e32 v121, v38, v178
	v_sub_u32_e32 v123, v38, v177
	v_mul_i32_i24_e32 v121, s98, v121
	v_mul_i32_i24_e32 v123, s98, v123
	v_cmp_gt_i32_e32 vcc, 1, v121
	v_cmp_gt_i32_e64 s[4:5], 1, v123
	v_mul_f32_e32 v120, 0x3db504f3, v120
	v_mul_f32_e32 v122, 0x3db504f3, v122
	v_cndmask_b32_e32 v120, 0, v120, vcc
	v_cndmask_b32_e64 v122, 0, v122, s[4:5]
	v_mul_f32_e32 v120, v120, v202
	v_mul_f32_e32 v122, v122, v203
	v_cvt_pk_bf16_f32 v120, v120, v120
	v_cvt_pk_bf16_f32 v122, v122, v122
	ds_write_b16 v1, v120 offset:39984
	ds_write_b16 v1, v122 offset:40256
	v_add_f32_e32 v124, v0, v112
	v_add_f32_e32 v126, v0, v113
	v_mul_f32_e32 v124, 0x3fb8aa3b, v124
	v_mul_f32_e32 v126, 0x3fb8aa3b, v126
	v_exp_f32_e32 v124, v124
	v_exp_f32_e32 v126, v126
	v_sub_u32_e32 v125, v38, v176
	v_sub_u32_e32 v127, v38, v175
	v_mul_i32_i24_e32 v125, s98, v125
	v_mul_i32_i24_e32 v127, s98, v127
	v_cmp_gt_i32_e32 vcc, 1, v125
	v_cmp_gt_i32_e64 s[4:5], 1, v127
	v_mul_f32_e32 v124, 0x3db504f3, v124
	v_mul_f32_e32 v126, 0x3db504f3, v126
	v_cndmask_b32_e32 v124, 0, v124, vcc
	v_cndmask_b32_e64 v126, 0, v126, s[4:5]
	v_mul_f32_e32 v124, v124, v204
	v_mul_f32_e32 v126, v126, v205
	v_cvt_pk_bf16_f32 v124, v124, v124
	v_cvt_pk_bf16_f32 v126, v126, v126
	ds_write_b16 v1, v124 offset:41616
	ds_write_b16 v1, v126 offset:41888
	v_add_f32_e32 v96, v0, v114
	v_add_f32_e32 v98, v0, v115
	v_mul_f32_e32 v96, 0x3fb8aa3b, v96
	v_mul_f32_e32 v98, 0x3fb8aa3b, v98
	v_exp_f32_e32 v96, v96
	v_exp_f32_e32 v98, v98
	v_sub_u32_e32 v97, v38, v174
	v_sub_u32_e32 v99, v38, v189
	v_mul_i32_i24_e32 v97, s98, v97
	v_mul_i32_i24_e32 v99, s98, v99
	v_cmp_gt_i32_e32 vcc, 1, v97
	v_cmp_gt_i32_e64 s[4:5], 1, v99
	v_mul_f32_e32 v96, 0x3db504f3, v96
	v_mul_f32_e32 v98, 0x3db504f3, v98
	v_cndmask_b32_e32 v96, 0, v96, vcc
	v_cndmask_b32_e64 v98, 0, v98, s[4:5]
	v_mul_f32_e32 v96, v96, v206
	v_mul_f32_e32 v98, v98, v207
	v_cvt_pk_bf16_f32 v96, v96, v96
	v_cvt_pk_bf16_f32 v98, v98, v98
	ds_write_b16 v1, v96 offset:42160
	ds_write_b16 v1, v98 offset:42432
; DI bf16 f2bf(float x) { return (bf16)(cvtpk(x, 0.f) & 0xffffu); }
; DI int crow(int i, int h) { return (i & 3) + 8 * (i >> 2) + 4 * h; }
; DI void mlstm_x3(const Params& p, LAS unsigned char* lds, int item, int tid_in, int lane_in, int wave) {
;     ...
;         for (int tt = 0; tt < 2; ++tt) { const int tj = 2 * eh + tt; const bool need = dir ? (tj >= ti) : (tj <= ti);
;             if (need) {
;                 const int scol = 32 * tj + r; const float as = d[scol];
; #pragma unroll
;                 for (int i = 0; i < 16; ++i) { const int trow = 32 * ti + crow(i, h); const bool ok = dir ? (scol >= trow) : (scol <= trow);
;                     const float e = ok ? __expf(as + d[128 + trow]) * KSCALE : 0.f;
;                     const float sv = (i & 1) ? __uint_as_float(spk[tt][i >> 1] & 0xffff0000u) : __uint_as_float(spk[tt][i >> 1] << 16); Ss[trow * MP + scol] = f2bf(sv * e); } } }
.LBB0_741:
	v_cndmask_b32_e64 v0, 0, 1, s[96:97]
	v_cndmask_b32_e64 v1, 0, 1, s[0:1]
	v_cndmask_b32_e64 v0, v0, v1, s[38:39]
	v_and_b32_e32 v0, 1, v0
	v_cmp_eq_u32_e32 vcc, 0, v0
	s_cbranch_vccnz .LBB0_775
	v_add_u32_e32 v1, s68, v37
	v_lshl_add_u32 v0, v1, 2, s8
	ds_read_b32 v0, v0
	s_cmp_lg_u64 s[38:39], 0
	s_cselect_b32 s98, 1, -1
	v_lshl_add_u32 v2, v1, 1, v192
	s_waitcnt lgkmcnt(0)
	v_add_f32_e32 v116, v0, v100
	v_add_f32_e32 v118, v0, v101
	v_mul_f32_e32 v116, 0x3fb8aa3b, v116
	v_mul_f32_e32 v118, 0x3fb8aa3b, v118
	v_exp_f32_e32 v116, v116
	v_exp_f32_e32 v118, v118
	v_sub_u32_e32 v117, v1, v188
	v_sub_u32_e32 v119, v1, v187
	v_mul_i32_i24_e32 v117, s98, v117
	v_mul_i32_i24_e32 v119, s98, v119
	v_cmp_gt_i32_e32 vcc, 1, v117
	v_cmp_gt_i32_e64 s[4:5], 1, v119
	v_mul_f32_e32 v116, 0x3db504f3, v116
	v_mul_f32_e32 v118, 0x3db504f3, v118
	v_cndmask_b32_e32 v116, 0, v116, vcc
	v_cndmask_b32_e64 v118, 0, v118, s[4:5]
	v_mul_f32_e32 v116, v116, v208
	v_mul_f32_e32 v118, v118, v209
	v_cvt_pk_bf16_f32 v116, v116, v116
	v_cvt_pk_bf16_f32 v118, v118, v118
	ds_write_b16 v2, v116 offset:35088
	ds_write_b16 v2, v118 offset:35360
	v_add_f32_e32 v120, v0, v102
	v_add_f32_e32 v122, v0, v103
	v_mul_f32_e32 v120, 0x3fb8aa3b, v120
	v_mul_f32_e32 v122, 0x3fb8aa3b, v122
	v_exp_f32_e32 v120, v120
	v_exp_f32_e32 v122, v122
	v_sub_u32_e32 v121, v1, v186
	v_sub_u32_e32 v123, v1, v185
	v_mul_i32_i24_e32 v121, s98, v121
	v_mul_i32_i24_e32 v123, s98, v123
	v_cmp_gt_i32_e32 vcc, 1, v121
	v_cmp_gt_i32_e64 s[4:5], 1, v123
	v_mul_f32_e32 v120, 0x3db504f3, v120
	v_mul_f32_e32 v122, 0x3db504f3, v122
	v_cndmask_b32_e32 v120, 0, v120, vcc
	v_cndmask_b32_e64 v122, 0, v122, s[4:5]
	v_mul_f32_e32 v120, v120, v210
	v_mul_f32_e32 v122, v122, v211
	v_cvt_pk_bf16_f32 v120, v120, v120
	v_cvt_pk_bf16_f32 v122, v122, v122
	ds_write_b16 v2, v120 offset:35632
	ds_write_b16 v2, v122 offset:35904
	v_add_f32_e32 v124, v0, v104
	v_add_f32_e32 v126, v0, v105
	v_mul_f32_e32 v124, 0x3fb8aa3b, v124
	v_mul_f32_e32 v126, 0x3fb8aa3b, v126
	v_exp_f32_e32 v124, v124
	v_exp_f32_e32 v126, v126
	v_sub_u32_e32 v125, v1, v184
	v_sub_u32_e32 v127, v1, v183
	v_mul_i32_i24_e32 v125, s98, v125
	v_mul_i32_i24_e32 v127, s98, v127
	v_cmp_gt_i32_e32 vcc, 1, v125
	v_cmp_gt_i32_e64 s[4:5], 1, v127
	v_mul_f32_e32 v124, 0x3db504f3, v124
	v_mul_f32_e32 v126, 0x3db504f3, v126
	v_cndmask_b32_e32 v124, 0, v124, vcc
	v_cndmask_b32_e64 v126, 0, v126, s[4:5]
	v_mul_f32_e32 v124, v124, v212
	v_mul_f32_e32 v126, v126, v213
	v_cvt_pk_bf16_f32 v124, v124, v124
	v_cvt_pk_bf16_f32 v126, v126, v126
	ds_write_b16 v2, v124 offset:37264
	ds_write_b16 v2, v126 offset:37536
	v_add_f32_e32 v96, v0, v106
	v_add_f32_e32 v98, v0, v107
	v_mul_f32_e32 v96, 0x3fb8aa3b, v96
	v_mul_f32_e32 v98, 0x3fb8aa3b, v98
	v_exp_f32_e32 v96, v96
	v_exp_f32_e32 v98, v98
	v_sub_u32_e32 v97, v1, v182
	v_sub_u32_e32 v99, v1, v181
	v_mul_i32_i24_e32 v97, s98, v97
	v_mul_i32_i24_e32 v99, s98, v99
	v_cmp_gt_i32_e32 vcc, 1, v97
	v_cmp_gt_i32_e64 s[4:5], 1, v99
	v_mul_f32_e32 v96, 0x3db504f3, v96
	v_mul_f32_e32 v98, 0x3db504f3, v98
	v_cndmask_b32_e32 v96, 0, v96, vcc
	v_cndmask_b32_e64 v98, 0, v98, s[4:5]
	v_mul_f32_e32 v96, v96, v214
	v_mul_f32_e32 v98, v98, v215
	v_cvt_pk_bf16_f32 v96, v96, v96
	v_cvt_pk_bf16_f32 v98, v98, v98
	ds_write_b16 v2, v96 offset:37808
	ds_write_b16 v2, v98 offset:38080
	v_add_f32_e32 v116, v0, v108
	v_add_f32_e32 v118, v0, v109
	v_mul_f32_e32 v116, 0x3fb8aa3b, v116
	v_mul_f32_e32 v118, 0x3fb8aa3b, v118
	v_exp_f32_e32 v116, v116
	v_exp_f32_e32 v118, v118
	v_sub_u32_e32 v117, v1, v180
	v_sub_u32_e32 v119, v1, v179
	v_mul_i32_i24_e32 v117, s98, v117
	v_mul_i32_i24_e32 v119, s98, v119
	v_cmp_gt_i32_e32 vcc, 1, v117
	v_cmp_gt_i32_e64 s[4:5], 1, v119
	v_mul_f32_e32 v116, 0x3db504f3, v116
	v_mul_f32_e32 v118, 0x3db504f3, v118
	v_cndmask_b32_e32 v116, 0, v116, vcc
	v_cndmask_b32_e64 v118, 0, v118, s[4:5]
	v_mul_f32_e32 v116, v116, v217
	v_mul_f32_e32 v118, v118, v218
	v_cvt_pk_bf16_f32 v116, v116, v116
	v_cvt_pk_bf16_f32 v118, v118, v118
	ds_write_b16 v2, v116 offset:39440
	ds_write_b16 v2, v118 offset:39712
	v_add_f32_e32 v120, v0, v110
	v_add_f32_e32 v122, v0, v111
	v_mul_f32_e32 v120, 0x3fb8aa3b, v120
	v_mul_f32_e32 v122, 0x3fb8aa3b, v122
	v_exp_f32_e32 v120, v120
	v_exp_f32_e32 v122, v122
	v_sub_u32_e32 v121, v1, v178
	v_sub_u32_e32 v123, v1, v177
	v_mul_i32_i24_e32 v121, s98, v121
	v_mul_i32_i24_e32 v123, s98, v123
	v_cmp_gt_i32_e32 vcc, 1, v121
	v_cmp_gt_i32_e64 s[4:5], 1, v123
	v_mul_f32_e32 v120, 0x3db504f3, v120
	v_mul_f32_e32 v122, 0x3db504f3, v122
	v_cndmask_b32_e32 v120, 0, v120, vcc
	v_cndmask_b32_e64 v122, 0, v122, s[4:5]
	v_mul_f32_e32 v120, v120, v219
	v_mul_f32_e32 v122, v122, v220
	v_cvt_pk_bf16_f32 v120, v120, v120
	v_cvt_pk_bf16_f32 v122, v122, v122
	ds_write_b16 v2, v120 offset:39984
	ds_write_b16 v2, v122 offset:40256
	v_add_f32_e32 v124, v0, v112
	v_add_f32_e32 v126, v0, v113
	v_mul_f32_e32 v124, 0x3fb8aa3b, v124
	v_mul_f32_e32 v126, 0x3fb8aa3b, v126
	v_exp_f32_e32 v124, v124
	v_exp_f32_e32 v126, v126
	v_sub_u32_e32 v125, v1, v176
	v_sub_u32_e32 v127, v1, v175
	v_mul_i32_i24_e32 v125, s98, v125
	v_mul_i32_i24_e32 v127, s98, v127
	v_cmp_gt_i32_e32 vcc, 1, v125
	v_cmp_gt_i32_e64 s[4:5], 1, v127
	v_mul_f32_e32 v124, 0x3db504f3, v124
	v_mul_f32_e32 v126, 0x3db504f3, v126
	v_cndmask_b32_e32 v124, 0, v124, vcc
	v_cndmask_b32_e64 v126, 0, v126, s[4:5]
	v_mul_f32_e32 v124, v124, v221
	v_mul_f32_e32 v126, v126, v222
	v_cvt_pk_bf16_f32 v124, v124, v124
	v_cvt_pk_bf16_f32 v126, v126, v126
	ds_write_b16 v2, v124 offset:41616
	ds_write_b16 v2, v126 offset:41888
	v_add_f32_e32 v96, v0, v114
	v_add_f32_e32 v98, v0, v115
	v_mul_f32_e32 v96, 0x3fb8aa3b, v96
	v_mul_f32_e32 v98, 0x3fb8aa3b, v98
	v_exp_f32_e32 v96, v96
	v_exp_f32_e32 v98, v98
	v_sub_u32_e32 v97, v1, v174
	v_sub_u32_e32 v99, v1, v189
	v_mul_i32_i24_e32 v97, s98, v97
	v_mul_i32_i24_e32 v99, s98, v99
	v_cmp_gt_i32_e32 vcc, 1, v97
	v_cmp_gt_i32_e64 s[4:5], 1, v99
	v_mul_f32_e32 v96, 0x3db504f3, v96
	v_mul_f32_e32 v98, 0x3db504f3, v98
	v_cndmask_b32_e32 v96, 0, v96, vcc
	v_cndmask_b32_e64 v98, 0, v98, s[4:5]
	v_mul_f32_e32 v96, v96, v223
	v_mul_f32_e32 v98, v98, v224
	v_cvt_pk_bf16_f32 v96, v96, v96
	v_cvt_pk_bf16_f32 v98, v98, v98
	ds_write_b16 v2, v96 offset:42160
	ds_write_b16 v2, v98 offset:42432

; __global__ void __launch_bounds__(512, 2) fwd_kernel(Params p) {
	.amdhsa_kernel _Z10fwd_kernel6Params
		.amdhsa_group_segment_fixed_size 0
		.amdhsa_private_segment_fixed_size 0
		.amdhsa_kernarg_size 440
		.amdhsa_user_sgpr_count 2
		.amdhsa_user_sgpr_dispatch_ptr 0
		.amdhsa_user_sgpr_queue_ptr 0
		.amdhsa_user_sgpr_kernarg_segment_ptr 1
		.amdhsa_user_sgpr_dispatch_id 0
		.amdhsa_user_sgpr_kernarg_preload_length 0
		.amdhsa_user_sgpr_kernarg_preload_offset 0
		.amdhsa_user_sgpr_private_segment_size 0
		.amdhsa_uses_dynamic_stack 0
		.amdhsa_enable_private_segment 0
		.amdhsa_system_sgpr_workgroup_id_x 1
		.amdhsa_system_sgpr_workgroup_id_y 0
		.amdhsa_system_sgpr_workgroup_id_z 0
		.amdhsa_system_sgpr_workgroup_info 0
		.amdhsa_system_vgpr_workitem_id 2
		.amdhsa_next_free_vgpr 255
		.amdhsa_next_free_sgpr 102
		.amdhsa_accum_offset 256
		.amdhsa_reserve_vcc 1
		.amdhsa_float_round_mode_32 0
		.amdhsa_float_round_mode_16_64 0
		.amdhsa_float_denorm_mode_32 3
		.amdhsa_float_denorm_mode_16_64 3
		.amdhsa_dx10_clamp 1
		.amdhsa_ieee_mode 1
		.amdhsa_fp16_overflow 0
		.amdhsa_tg_split 0
		.amdhsa_exception_fp_ieee_invalid_op 0
		.amdhsa_exception_fp_denorm_src 0
		.amdhsa_exception_fp_ieee_div_zero 0
		.amdhsa_exception_fp_ieee_overflow 0
		.amdhsa_exception_fp_ieee_underflow 0
		.amdhsa_exception_fp_ieee_inexact 0
		.amdhsa_exception_int_div_zero 0
	.end_amdhsa_kernel

; __global__ void __launch_bounds__(512, 2) fwd_kernel(Params p) {
amdhsa.kernels:
  - .agpr_count:     0
    .args:
      - .offset:         0
        .size:           184
        .value_kind:     by_value
      - .offset:         184
        .size:           4
        .value_kind:     hidden_block_count_x
      - .offset:         188
        .size:           4
        .value_kind:     hidden_block_count_y
      - .offset:         192
        .size:           4
        .value_kind:     hidden_block_count_z
      - .offset:         196
        .size:           2
        .value_kind:     hidden_group_size_x
      - .offset:         198
        .size:           2
        .value_kind:     hidden_group_size_y
      - .offset:         200
        .size:           2
        .value_kind:     hidden_group_size_z
      - .offset:         202
        .size:           2
        .value_kind:     hidden_remainder_x
      - .offset:         204
        .size:           2
        .value_kind:     hidden_remainder_y
      - .offset:         206
        .size:           2
        .value_kind:     hidden_remainder_z
      - .offset:         224
        .size:           8
        .value_kind:     hidden_global_offset_x
      - .offset:         232
        .size:           8
        .value_kind:     hidden_global_offset_y
      - .offset:         240
        .size:           8
        .value_kind:     hidden_global_offset_z
      - .offset:         248
        .size:           2
        .value_kind:     hidden_grid_dims
      - .offset:         272
        .size:           8
        .value_kind:     hidden_multigrid_sync_arg
      - .offset:         304
        .size:           4
        .value_kind:     hidden_dynamic_lds_size
    .group_segment_fixed_size: 0
    .kernarg_segment_align: 8
    .kernarg_segment_size: 440
    .language:       OpenCL C
    .language_version:
      - 2
      - 0
    .max_flat_workgroup_size: 512
    .name:           _Z10fwd_kernel6Params
    .private_segment_fixed_size: 0
    .sgpr_count:     108
    .sgpr_spill_count: 179
    .symbol:         _Z10fwd_kernel6Params.kd
    .uniform_work_group_size: 1
    .uses_dynamic_stack: false
    .vgpr_count:     255
    .vgpr_spill_count: 0
    .wavefront_size: 64
